# v27 + attention merge done by the 128 side workgroups that have half a GEMM unit less (the 64 most loaded ones skip it)
# speedup vs baseline: 1.0189x; 1.0089x over previous
; __device__ __forceinline__ void store16_wt(void* p, u32x4 v) { asm volatile("global_store_dwordx4 %0, %1, off sc1\n\ts_nop 1" :: "v"(p), "v"(v) : "memory"); }
; #define MRG(F) o.F = pk_bf16((w0 * bflo(a.F) + w1 * bflo(bq.F) + w2 * bflo(cq.F)) * bflo(gq.F), (w0 * bfhi(a.F) + w1 * bfhi(bq.F) + w2 * bfhi(cq.F)) * bfhi(gq.F))
; __device__ __forceinline__ void merge_phase(u16* OG, const float* LSE, const u16* AG, int bid, int nb) {
;     for (int idx = bid * 512 + threadIdx.x; idx < TT * 64; idx += nb * 512) {
;         const int tok = idx >> 6, h = (idx >> 3) & 7, ch = idx & 7; const size_t off = (size_t)tok * 512 + h * 64 + 8 * ch;
;         const float l0 = LSE[(size_t)tok * 8 + h], l1 = LSE[(size_t)TT * 8 + (size_t)tok * 8 + h], l2 = LSE[(size_t)2 * TT * 8 + (size_t)tok * 8 + h];
;         const float m = fmaxf(l0, fmaxf(l1, l2)); float w0 = __builtin_amdgcn_exp2f(l0 - m), w1 = __builtin_amdgcn_exp2f(l1 - m), w2 = __builtin_amdgcn_exp2f(l2 - m);
;         const float inv = 1.0f / (w0 + w1 + w2); w0 *= inv; w1 *= inv; w2 *= inv;
;         const u32x4 a = *(const u32x4*)(OG + off), bq = *(const u32x4*)(OG + (size_t)TT * 512 + off), cq = *(const u32x4*)(OG + (size_t)2 * TT * 512 + off), gq = *(const u32x4*)(AG + off);
;         u32x4 o;
;     ...
;         MRG(x); MRG(y); MRG(z); MRG(w);
;     ...
;         store16_wt(OG + off, o);
;     }
; __global__ void __launch_bounds__(512, 2) fwd_megakernel(Args a) {
;     ...
;                 merge_phase((u16*)(dout + DO_OG), (const float*)(ws + WS_COS), (const u16*)(dout + DO_AG), bx - 64, 192);
.Ls3d_rel:
.Ls3d_skip:
	s_mov_b64 exec, s[6:7]
	s_barrier
	s_add_u32 s4, s76, 0x1000000
	s_addc_u32 s5, s77, 0
	s_lshl_b32 s6, s2, 9
	v_add_u32_e32 v1, s6, v188
	v_add_u32_e32 v0, 0xffff0000, v1
	s_mov_b32 s16, 0x100000
	v_cmp_gt_u32_e32 vcc, s16, v0
	s_and_saveexec_b64 s[6:7], vcc
	s_cbranch_execz .LBB0_450
	s_add_u32 s8, s78, 0x1b00000
	s_addc_u32 s9, s79, 0
	s_add_u32 s10, s76, 0x3000000
	s_addc_u32 s11, s77, 0
	s_add_u32 s12, s76, 0x2000000
	s_addc_u32 s13, s77, 0
	v_add_u32_e32 v2, 0xfffe0000, v1
	v_lshlrev_b32_e32 v3, 3, v0
	s_mov_b64 s[14:15], 0
	v_mov_b32_e32 v1, 0
	s_mov_b32 s17, 0x80000
	s_mov_b32 s18, 0xeffff
.LBB0_449:
	v_add_u32_e32 v2, 0x10000, v2
	v_ashrrev_i32_e32 v4, 6, v2
	v_ashrrev_i32_e32 v5, 31, v4
	v_bfe_u32 v0, v2, 3, 3
	v_lshlrev_b64 v[6:7], 9, v[4:5]
	v_lshlrev_b64 v[4:5], 5, v[4:5]
	v_lshlrev_b32_e32 v9, 6, v0
	v_lshlrev_b32_e32 v0, 2, v0
	v_lshl_add_u64 v[4:5], s[8:9], 0, v[4:5]
	v_lshl_add_u64 v[20:21], v[4:5], 0, v[0:1]
	v_and_b32_e32 v8, 56, v3
	v_add_co_u32_e32 v22, vcc, s17, v20
	v_or3_b32 v6, v6, v9, v8
	s_nop 0
	v_addc_co_u32_e32 v23, vcc, 0, v21, vcc
	v_lshlrev_b64 v[4:5], 1, v[6:7]
	v_add_co_u32_e32 v24, vcc, s16, v20
	v_lshl_add_u64 v[26:27], s[76:77], 0, v[4:5]
	s_nop 0
	v_addc_co_u32_e32 v25, vcc, 0, v21, vcc
	v_lshl_add_u64 v[28:29], s[4:5], 0, v[4:5]
	v_lshl_add_u64 v[30:31], s[12:13], 0, v[4:5]
	v_lshl_add_u64 v[32:33], s[10:11], 0, v[4:5]
	global_load_dword v0, v[20:21], off sc1
	global_load_dword v40, v[22:23], off sc1
	global_load_dword v41, v[24:25], off sc1
	global_load_dwordx4 v[4:7], v[28:29], off sc1
	global_load_dwordx4 v[8:11], v[26:27], off sc1
	global_load_dwordx4 v[12:15], v[30:31], off sc1
	global_load_dwordx4 v[16:19], v[32:33], off sc1
	v_add_u32_e32 v3, 0x80000, v3
	s_waitcnt vmcnt(4)
	v_max3_f32 v42, v0, v40, v41
	v_sub_f32_e32 v0, v0, v42
	s_waitcnt vmcnt(3)
	v_lshlrev_b32_e32 v20, 16, v4
	s_waitcnt vmcnt(2)
	v_and_b32_e32 v21, 0xffff0000, v8
	s_waitcnt vmcnt(0)
	v_lshlrev_b32_e32 v36, 16, v18
	v_and_b32_e32 v37, 0xffff0000, v18
	v_sub_f32_e32 v18, v40, v42
	v_lshlrev_b32_e32 v22, 16, v8
	v_and_b32_e32 v23, 0xffff0000, v4
	v_lshlrev_b32_e32 v24, 16, v12
	v_and_b32_e32 v25, 0xffff0000, v12
	v_lshlrev_b32_e32 v28, 16, v16
	v_and_b32_e32 v29, 0xffff0000, v16
	v_and_b32_e32 v31, 0xffff0000, v9
	v_lshlrev_b32_e32 v4, 16, v9
	v_lshlrev_b32_e32 v8, 16, v13
	v_and_b32_e32 v9, 0xffff0000, v13
	v_lshlrev_b32_e32 v12, 16, v17
	v_and_b32_e32 v13, 0xffff0000, v17
	v_lshlrev_b32_e32 v16, 16, v6
	v_and_b32_e32 v17, 0xffff0000, v10
	v_lshlrev_b32_e32 v32, 16, v10
	v_and_b32_e32 v33, 0xffff0000, v6
	v_lshlrev_b32_e32 v34, 16, v14
	v_and_b32_e32 v35, 0xffff0000, v14
	v_and_b32_e32 v39, 0xffff0000, v11
	v_lshlrev_b32_e32 v6, 16, v11
	v_lshlrev_b32_e32 v10, 16, v15
	v_and_b32_e32 v11, 0xffff0000, v15
	v_lshlrev_b32_e32 v14, 16, v19
	v_and_b32_e32 v15, 0xffff0000, v19
	v_sub_f32_e32 v40, v41, v42
	v_exp_f32_e32 v19, v0
	v_exp_f32_e32 v18, v18
	v_exp_f32_e32 v40, v40
	v_lshlrev_b32_e32 v30, 16, v5
	v_and_b32_e32 v5, 0xffff0000, v5
	v_add_f32_e32 v0, v19, v18
	v_add_f32_e32 v0, v40, v0
	v_div_scale_f32 v41, s[20:21], v0, v0, 1.0
	v_rcp_f32_e32 v43, v41
	v_div_scale_f32 v42, vcc, 1.0, v0, 1.0
	v_lshlrev_b32_e32 v38, 16, v7
	v_fma_f32 v44, -v41, v43, 1.0
	v_fmac_f32_e32 v43, v44, v43
	v_mul_f32_e32 v44, v42, v43
	v_fma_f32 v45, -v41, v44, v42
	v_fmac_f32_e32 v44, v45, v43
	v_fma_f32 v41, -v41, v44, v42
	v_div_fmas_f32 v41, v41, v43, v44
	v_div_fixup_f32 v0, v41, v0, 1.0
	v_and_b32_e32 v7, 0xffff0000, v7
	v_pk_mul_f32 v[18:19], v[18:19], v[0:1] op_sel_hi:[1,0]
	v_mul_f32_e32 v40, v40, v0
	v_pk_mul_f32 v[22:23], v[18:19], v[22:23] op_sel:[1,0] op_sel_hi:[0,1]
	v_pk_mul_f32 v[4:5], v[18:19], v[4:5] op_sel:[1,0] op_sel_hi:[0,1]
	v_pk_mul_f32 v[32:33], v[18:19], v[32:33] op_sel:[1,0] op_sel_hi:[0,1]
	v_pk_mul_f32 v[6:7], v[18:19], v[6:7] op_sel:[1,0] op_sel_hi:[0,1]
	v_pk_fma_f32 v[20:21], v[18:19], v[20:21], v[22:23]
	v_pk_fma_f32 v[4:5], v[18:19], v[30:31], v[4:5]
	v_pk_fma_f32 v[16:17], v[18:19], v[16:17], v[32:33]
	v_pk_fma_f32 v[6:7], v[18:19], v[38:39], v[6:7]
	v_pk_fma_f32 v[18:19], v[40:41], v[24:25], v[20:21] op_sel_hi:[0,1,1]
	v_pk_fma_f32 v[4:5], v[40:41], v[8:9], v[4:5] op_sel_hi:[0,1,1]
	v_pk_fma_f32 v[8:9], v[40:41], v[34:35], v[16:17] op_sel_hi:[0,1,1]
	v_pk_fma_f32 v[6:7], v[40:41], v[10:11], v[6:7] op_sel_hi:[0,1,1]
	v_pk_mul_f32 v[10:11], v[18:19], v[28:29]
	v_pk_mul_f32 v[12:13], v[4:5], v[12:13]
	v_pk_mul_f32 v[8:9], v[8:9], v[36:37]
	v_pk_mul_f32 v[14:15], v[6:7], v[14:15]
	v_cvt_pk_bf16_f32 v4, v10, v11
	v_cvt_pk_bf16_f32 v5, v12, v13
	v_cvt_pk_bf16_f32 v6, v8, v9
	v_cvt_pk_bf16_f32 v7, v14, v15
	global_store_dwordx4 v[26:27], v[4:7], off sc1
	s_nop 1
	v_cmp_lt_i32_e32 vcc, s18, v2
	s_or_b64 s[14:15], vcc, s[14:15]
	s_andn2_b64 exec, exec, s[14:15]
	s_cbranch_execnz .LBB0_449
